# v154 + P9 epilogue: output-row addresses 2..8 derived from address 1 plus SGPR row-stride multiples (28 fewer VALU ops per unit incl. 14 v_mad_u64_u32)
# baseline (speedup 1.0000x reference)
.LBB0_513:
	v_mov_b64_e32 v[164:165], s[16:17]
	v_mad_u64_u32 v[188:189], s[0:1], v162, s64, v[164:165]
	v_lshl_or_b32 v186, s65, 7, v182
	v_mov_b32_e32 v162, v189
	v_ashrrev_i32_e32 v187, 31, v186
	v_mad_u64_u32 v[162:163], s[0:1], v163, s64, v[162:163]
	s_waitcnt lgkmcnt(0)
	v_pk_mul_f32 v[124:125], v[124:125], v[170:171] op_sel_hi:[1,0]
	v_mov_b32_e32 v189, v162
	v_lshlrev_b64 v[162:163], 1, v[186:187]
	v_mul_f32_e32 v186, 0xbfb8aa3b, v124
	v_exp_f32_e32 v190, v186
	v_mul_f32_e32 v186, 0xbfb8aa3b, v125
	v_exp_f32_e32 v191, v186
	v_pk_mul_f32 v[126:127], v[126:127], v[170:171] op_sel_hi:[1,0]
	v_lshl_add_u64 v[186:187], v[188:189], 0, v[162:163]
	v_mov_b64_e32 v[252:253], v[186:187]
	s_mov_b32 s93, 0
	v_add_f32_e32 v188, 1.0, v190
	v_add_f32_e32 v189, 1.0, v191
	v_mul_f32_e32 v190, 0xbfb8aa3b, v126
	v_mul_f32_e32 v191, 0xbfb8aa3b, v127
	v_rcp_f32_e32 v188, v188
	v_rcp_f32_e32 v189, v189
	v_exp_f32_e32 v190, v190
	v_exp_f32_e32 v191, v191
	v_pk_mul_f32 v[116:117], v[116:117], v[170:171] op_sel_hi:[1,0]
	v_pk_mul_f32 v[124:125], v[124:125], v[188:189]
	v_add_f32_e32 v188, 1.0, v190
	v_add_f32_e32 v189, 1.0, v191
	v_rcp_f32_e32 v188, v188
	v_rcp_f32_e32 v189, v189
	v_pk_mul_f32 v[116:117], v[116:117], v[124:125]
	v_pk_mul_f32 v[120:121], v[120:121], v[170:171] op_sel_hi:[1,0]
	v_cvt_pk_bf16_f32 v116, v116, v117
	v_pk_mul_f32 v[124:125], v[126:127], v[188:189]
	v_pk_mul_f32 v[118:119], v[118:119], v[170:171] op_sel_hi:[1,0]
	v_mul_f32_e32 v117, 0xbfb8aa3b, v120
	v_pk_mul_f32 v[118:119], v[118:119], v[124:125]
	v_exp_f32_e32 v124, v117
	v_mul_f32_e32 v117, 0xbfb8aa3b, v121
	v_exp_f32_e32 v125, v117
	v_pk_mul_f32 v[122:123], v[122:123], v[170:171] op_sel_hi:[1,0]
	v_cvt_pk_bf16_f32 v117, v118, v119
	v_add_f32_e32 v118, 1.0, v124
	v_add_f32_e32 v119, 1.0, v125
	v_mul_f32_e32 v124, 0xbfb8aa3b, v122
	v_mul_f32_e32 v125, 0xbfb8aa3b, v123
	v_rcp_f32_e32 v118, v118
	v_rcp_f32_e32 v119, v119
	v_exp_f32_e32 v124, v124
	v_exp_f32_e32 v125, v125
	v_pk_mul_f32 v[112:113], v[112:113], v[170:171] op_sel_hi:[1,0]
	v_pk_mul_f32 v[118:119], v[120:121], v[118:119]
	v_add_f32_e32 v120, 1.0, v124
	v_add_f32_e32 v121, 1.0, v125
	v_rcp_f32_e32 v120, v120
	v_rcp_f32_e32 v121, v121
	v_pk_mul_f32 v[112:113], v[112:113], v[118:119]
	v_pk_mul_f32 v[114:115], v[114:115], v[170:171] op_sel_hi:[1,0]
	v_cvt_pk_bf16_f32 v118, v112, v113
	v_pk_mul_f32 v[112:113], v[122:123], v[120:121]
	v_pk_mul_f32 v[108:109], v[108:109], v[170:171] op_sel:[0,1]
	v_pk_mul_f32 v[112:113], v[114:115], v[112:113]
	v_pk_mul_f32 v[110:111], v[110:111], v[170:171] op_sel:[0,1]
	v_cvt_pk_bf16_f32 v119, v112, v113
	v_mul_f32_e32 v114, 0xbfb8aa3b, v108
	v_mul_f32_e32 v115, 0xbfb8aa3b, v109
	v_exp_f32_e32 v114, v114
	v_exp_f32_e32 v115, v115
	global_store_dwordx4 v[186:187], v[116:119], off
	v_pk_mul_f32 v[100:101], v[100:101], v[170:171] op_sel:[0,1]
	v_add_f32_e32 v114, 1.0, v114
	v_add_f32_e32 v115, 1.0, v115
	v_mul_f32_e32 v116, 0xbfb8aa3b, v110
	v_mul_f32_e32 v117, 0xbfb8aa3b, v111
	v_rcp_f32_e32 v114, v114
	v_rcp_f32_e32 v115, v115
	v_exp_f32_e32 v116, v116
	v_exp_f32_e32 v117, v117
	v_pk_mul_f32 v[104:105], v[104:105], v[170:171] op_sel:[0,1]
	v_pk_mul_f32 v[108:109], v[108:109], v[114:115]
	v_add_f32_e32 v114, 1.0, v116
	v_add_f32_e32 v115, 1.0, v117
	v_rcp_f32_e32 v114, v114
	v_rcp_f32_e32 v115, v115
	v_pk_mul_f32 v[100:101], v[100:101], v[108:109]
	v_pk_mul_f32 v[102:103], v[102:103], v[170:171] op_sel:[0,1]
	v_cvt_pk_bf16_f32 v100, v100, v101
	v_pk_mul_f32 v[108:109], v[110:111], v[114:115]
	v_mul_f32_e32 v101, 0xbfb8aa3b, v104
	v_pk_mul_f32 v[102:103], v[102:103], v[108:109]
	v_exp_f32_e32 v108, v101
	v_mul_f32_e32 v101, 0xbfb8aa3b, v105
	v_exp_f32_e32 v109, v101
	v_pk_mul_f32 v[106:107], v[106:107], v[170:171] op_sel:[0,1]
	v_cvt_pk_bf16_f32 v101, v102, v103
	v_add_f32_e32 v102, 1.0, v108
	v_add_f32_e32 v103, 1.0, v109
	v_mul_f32_e32 v108, 0xbfb8aa3b, v106
	v_mul_f32_e32 v109, 0xbfb8aa3b, v107
	v_rcp_f32_e32 v102, v102
	v_rcp_f32_e32 v103, v103
	v_exp_f32_e32 v108, v108
	v_exp_f32_e32 v109, v109
	v_pk_mul_f32 v[96:97], v[96:97], v[170:171] op_sel:[0,1]
	v_pk_mul_f32 v[102:103], v[104:105], v[102:103]
	v_add_f32_e32 v104, 1.0, v108
	v_add_f32_e32 v105, 1.0, v109
	v_rcp_f32_e32 v104, v104
	v_rcp_f32_e32 v105, v105
	v_pk_mul_f32 v[96:97], v[96:97], v[102:103]
	v_pk_mul_f32 v[98:99], v[98:99], v[170:171] op_sel:[0,1]
	v_cvt_pk_bf16_f32 v102, v96, v97
	v_pk_mul_f32 v[96:97], v[106:107], v[104:105]
	v_pk_mul_f32 v[92:93], v[92:93], v[168:169] op_sel_hi:[1,0]
	v_pk_mul_f32 v[96:97], v[98:99], v[96:97]
	s_mul_i32 s92, s64, 16
	v_lshl_add_u64 v[112:113], v[252:253], 0, s[92:93]
	v_cvt_pk_bf16_f32 v103, v96, v97
	v_mul_f32_e32 v98, 0xbfb8aa3b, v92
	v_mul_f32_e32 v99, 0xbfb8aa3b, v93
	v_exp_f32_e32 v98, v98
	v_exp_f32_e32 v99, v99
	v_pk_mul_f32 v[94:95], v[94:95], v[168:169] op_sel_hi:[1,0]
	global_store_dwordx4 v[112:113], v[100:103], off
	v_add_f32_e32 v98, 1.0, v98
	v_add_f32_e32 v99, 1.0, v99
	v_mul_f32_e32 v100, 0xbfb8aa3b, v94
	v_mul_f32_e32 v101, 0xbfb8aa3b, v95
	v_rcp_f32_e32 v98, v98
	v_rcp_f32_e32 v99, v99
	v_exp_f32_e32 v100, v100
	v_exp_f32_e32 v101, v101
	v_pk_mul_f32 v[84:85], v[84:85], v[168:169] op_sel_hi:[1,0]
	v_pk_mul_f32 v[92:93], v[92:93], v[98:99]
	v_add_f32_e32 v98, 1.0, v100
	v_add_f32_e32 v99, 1.0, v101
	v_rcp_f32_e32 v98, v98
	v_rcp_f32_e32 v99, v99
	v_pk_mul_f32 v[84:85], v[84:85], v[92:93]
	v_pk_mul_f32 v[88:89], v[88:89], v[168:169] op_sel_hi:[1,0]
	v_cvt_pk_bf16_f32 v84, v84, v85
	v_pk_mul_f32 v[92:93], v[94:95], v[98:99]
	v_pk_mul_f32 v[86:87], v[86:87], v[168:169] op_sel_hi:[1,0]
	v_mul_f32_e32 v85, 0xbfb8aa3b, v88
	v_pk_mul_f32 v[86:87], v[86:87], v[92:93]
	v_exp_f32_e32 v92, v85
	v_mul_f32_e32 v85, 0xbfb8aa3b, v89
	v_exp_f32_e32 v93, v85
	v_pk_mul_f32 v[90:91], v[90:91], v[168:169] op_sel_hi:[1,0]
	v_cvt_pk_bf16_f32 v85, v86, v87
	v_add_f32_e32 v86, 1.0, v92
	v_add_f32_e32 v87, 1.0, v93
	v_mul_f32_e32 v92, 0xbfb8aa3b, v90
	v_mul_f32_e32 v93, 0xbfb8aa3b, v91
	v_rcp_f32_e32 v86, v86
	v_rcp_f32_e32 v87, v87
	v_exp_f32_e32 v92, v92
	v_exp_f32_e32 v93, v93
	v_pk_mul_f32 v[80:81], v[80:81], v[168:169] op_sel_hi:[1,0]
	v_pk_mul_f32 v[86:87], v[88:89], v[86:87]
	v_add_f32_e32 v88, 1.0, v92
	v_add_f32_e32 v89, 1.0, v93
	v_rcp_f32_e32 v88, v88
	v_rcp_f32_e32 v89, v89
	v_pk_mul_f32 v[80:81], v[80:81], v[86:87]
	v_pk_mul_f32 v[82:83], v[82:83], v[168:169] op_sel_hi:[1,0]
	v_cvt_pk_bf16_f32 v86, v80, v81
	v_pk_mul_f32 v[80:81], v[90:91], v[88:89]
	v_pk_mul_f32 v[76:77], v[76:77], v[168:169] op_sel:[0,1]
	v_pk_mul_f32 v[80:81], v[82:83], v[80:81]
	s_mul_i32 s92, s64, 32
	v_lshl_add_u64 v[96:97], v[252:253], 0, s[92:93]
	v_cvt_pk_bf16_f32 v87, v80, v81
	v_mul_f32_e32 v82, 0xbfb8aa3b, v76
	v_mul_f32_e32 v83, 0xbfb8aa3b, v77
	v_exp_f32_e32 v82, v82
	v_exp_f32_e32 v83, v83
	v_pk_mul_f32 v[78:79], v[78:79], v[168:169] op_sel:[0,1]
	global_store_dwordx4 v[96:97], v[84:87], off
	v_add_f32_e32 v82, 1.0, v82
	v_add_f32_e32 v83, 1.0, v83
	v_mul_f32_e32 v84, 0xbfb8aa3b, v78
	v_mul_f32_e32 v85, 0xbfb8aa3b, v79
	v_rcp_f32_e32 v82, v82
	v_rcp_f32_e32 v83, v83
	v_exp_f32_e32 v84, v84
	v_exp_f32_e32 v85, v85
	v_pk_mul_f32 v[68:69], v[68:69], v[168:169] op_sel:[0,1]
	v_pk_mul_f32 v[76:77], v[76:77], v[82:83]
	v_add_f32_e32 v82, 1.0, v84
	v_add_f32_e32 v83, 1.0, v85
	v_rcp_f32_e32 v82, v82
	v_rcp_f32_e32 v83, v83
	v_pk_mul_f32 v[68:69], v[68:69], v[76:77]
	v_pk_mul_f32 v[72:73], v[72:73], v[168:169] op_sel:[0,1]
	v_cvt_pk_bf16_f32 v68, v68, v69
	v_pk_mul_f32 v[76:77], v[78:79], v[82:83]
	v_pk_mul_f32 v[70:71], v[70:71], v[168:169] op_sel:[0,1]
	v_mul_f32_e32 v69, 0xbfb8aa3b, v72
	v_pk_mul_f32 v[70:71], v[70:71], v[76:77]
	v_exp_f32_e32 v76, v69
	v_mul_f32_e32 v69, 0xbfb8aa3b, v73
	v_exp_f32_e32 v77, v69
	v_pk_mul_f32 v[74:75], v[74:75], v[168:169] op_sel:[0,1]
	v_cvt_pk_bf16_f32 v69, v70, v71
	v_add_f32_e32 v70, 1.0, v76
	v_add_f32_e32 v71, 1.0, v77
	v_mul_f32_e32 v76, 0xbfb8aa3b, v74
	v_mul_f32_e32 v77, 0xbfb8aa3b, v75
	v_rcp_f32_e32 v70, v70
	v_rcp_f32_e32 v71, v71
	v_exp_f32_e32 v76, v76
	v_exp_f32_e32 v77, v77
	v_pk_mul_f32 v[64:65], v[64:65], v[168:169] op_sel:[0,1]
	v_pk_mul_f32 v[70:71], v[72:73], v[70:71]
	v_add_f32_e32 v72, 1.0, v76
	v_add_f32_e32 v73, 1.0, v77
	v_rcp_f32_e32 v72, v72
	v_rcp_f32_e32 v73, v73
	v_pk_mul_f32 v[64:65], v[64:65], v[70:71]
	v_pk_mul_f32 v[66:67], v[66:67], v[168:169] op_sel:[0,1]
	v_cvt_pk_bf16_f32 v70, v64, v65
	v_pk_mul_f32 v[64:65], v[74:75], v[72:73]
	v_pk_mul_f32 v[60:61], v[60:61], v[160:161] op_sel_hi:[1,0]
	v_pk_mul_f32 v[64:65], v[66:67], v[64:65]
	s_mul_i32 s92, s64, 48
	v_lshl_add_u64 v[80:81], v[252:253], 0, s[92:93]
	v_cvt_pk_bf16_f32 v71, v64, v65
	v_mul_f32_e32 v66, 0xbfb8aa3b, v60
	v_mul_f32_e32 v67, 0xbfb8aa3b, v61
	v_exp_f32_e32 v66, v66
	v_exp_f32_e32 v67, v67
	v_pk_mul_f32 v[62:63], v[62:63], v[160:161] op_sel_hi:[1,0]
	global_store_dwordx4 v[80:81], v[68:71], off
	v_add_f32_e32 v66, 1.0, v66
	v_add_f32_e32 v67, 1.0, v67
	v_mul_f32_e32 v68, 0xbfb8aa3b, v62
	v_mul_f32_e32 v69, 0xbfb8aa3b, v63
	v_rcp_f32_e32 v66, v66
	v_rcp_f32_e32 v67, v67
	v_exp_f32_e32 v68, v68
	v_exp_f32_e32 v69, v69
	v_pk_mul_f32 v[52:53], v[52:53], v[160:161] op_sel_hi:[1,0]
	v_pk_mul_f32 v[60:61], v[60:61], v[66:67]
	v_add_f32_e32 v66, 1.0, v68
	v_add_f32_e32 v67, 1.0, v69
	v_rcp_f32_e32 v66, v66
	v_rcp_f32_e32 v67, v67
	v_pk_mul_f32 v[52:53], v[52:53], v[60:61]
	v_pk_mul_f32 v[56:57], v[56:57], v[160:161] op_sel_hi:[1,0]
	v_cvt_pk_bf16_f32 v52, v52, v53
	v_pk_mul_f32 v[60:61], v[62:63], v[66:67]
	v_pk_mul_f32 v[54:55], v[54:55], v[160:161] op_sel_hi:[1,0]
	v_mul_f32_e32 v53, 0xbfb8aa3b, v56
	v_pk_mul_f32 v[54:55], v[54:55], v[60:61]
	v_exp_f32_e32 v60, v53
	v_mul_f32_e32 v53, 0xbfb8aa3b, v57
	v_exp_f32_e32 v61, v53
	v_pk_mul_f32 v[58:59], v[58:59], v[160:161] op_sel_hi:[1,0]
	v_cvt_pk_bf16_f32 v53, v54, v55
	v_add_f32_e32 v54, 1.0, v60
	v_add_f32_e32 v55, 1.0, v61
	v_mul_f32_e32 v60, 0xbfb8aa3b, v58
	v_mul_f32_e32 v61, 0xbfb8aa3b, v59
	v_rcp_f32_e32 v54, v54
	v_rcp_f32_e32 v55, v55
	v_exp_f32_e32 v60, v60
	v_exp_f32_e32 v61, v61
	v_pk_mul_f32 v[48:49], v[48:49], v[160:161] op_sel_hi:[1,0]
	v_pk_mul_f32 v[54:55], v[56:57], v[54:55]
	v_add_f32_e32 v56, 1.0, v60
	v_add_f32_e32 v57, 1.0, v61
	v_rcp_f32_e32 v56, v56
	v_rcp_f32_e32 v57, v57
	v_pk_mul_f32 v[48:49], v[48:49], v[54:55]
	v_pk_mul_f32 v[50:51], v[50:51], v[160:161] op_sel_hi:[1,0]
	v_cvt_pk_bf16_f32 v54, v48, v49
	v_pk_mul_f32 v[48:49], v[58:59], v[56:57]
	v_pk_mul_f32 v[44:45], v[44:45], v[160:161] op_sel:[0,1]
	v_pk_mul_f32 v[48:49], v[50:51], v[48:49]
	s_mul_i32 s92, s64, 128
	v_lshl_add_u64 v[64:65], v[252:253], 0, s[92:93]
	v_cvt_pk_bf16_f32 v55, v48, v49
	v_mul_f32_e32 v50, 0xbfb8aa3b, v44
	v_mul_f32_e32 v51, 0xbfb8aa3b, v45
	v_exp_f32_e32 v50, v50
	v_exp_f32_e32 v51, v51
	v_pk_mul_f32 v[46:47], v[46:47], v[160:161] op_sel:[0,1]
	global_store_dwordx4 v[64:65], v[52:55], off
	v_add_f32_e32 v50, 1.0, v50
	v_add_f32_e32 v51, 1.0, v51
	v_mul_f32_e32 v52, 0xbfb8aa3b, v46
	v_mul_f32_e32 v53, 0xbfb8aa3b, v47
	v_rcp_f32_e32 v50, v50
	v_rcp_f32_e32 v51, v51
	v_exp_f32_e32 v52, v52
	v_exp_f32_e32 v53, v53
	v_pk_mul_f32 v[36:37], v[36:37], v[160:161] op_sel:[0,1]
	v_pk_mul_f32 v[44:45], v[44:45], v[50:51]
	v_add_f32_e32 v50, 1.0, v52
	v_add_f32_e32 v51, 1.0, v53
	v_rcp_f32_e32 v50, v50
	v_rcp_f32_e32 v51, v51
	v_pk_mul_f32 v[36:37], v[36:37], v[44:45]
	v_pk_mul_f32 v[40:41], v[40:41], v[160:161] op_sel:[0,1]
	v_cvt_pk_bf16_f32 v36, v36, v37
	v_pk_mul_f32 v[44:45], v[46:47], v[50:51]
	v_pk_mul_f32 v[38:39], v[38:39], v[160:161] op_sel:[0,1]
	v_mul_f32_e32 v37, 0xbfb8aa3b, v40
	v_pk_mul_f32 v[38:39], v[38:39], v[44:45]
	v_exp_f32_e32 v44, v37
	v_mul_f32_e32 v37, 0xbfb8aa3b, v41
	v_exp_f32_e32 v45, v37
	v_pk_mul_f32 v[42:43], v[42:43], v[160:161] op_sel:[0,1]
	v_cvt_pk_bf16_f32 v37, v38, v39
	v_add_f32_e32 v38, 1.0, v44
	v_add_f32_e32 v39, 1.0, v45
	v_mul_f32_e32 v44, 0xbfb8aa3b, v42
	v_mul_f32_e32 v45, 0xbfb8aa3b, v43
	v_rcp_f32_e32 v38, v38
	v_rcp_f32_e32 v39, v39
	v_exp_f32_e32 v44, v44
	v_exp_f32_e32 v45, v45
	v_pk_mul_f32 v[32:33], v[32:33], v[160:161] op_sel:[0,1]
	v_pk_mul_f32 v[38:39], v[40:41], v[38:39]
	v_add_f32_e32 v40, 1.0, v44
	v_add_f32_e32 v41, 1.0, v45
	v_rcp_f32_e32 v40, v40
	v_rcp_f32_e32 v41, v41
	v_pk_mul_f32 v[32:33], v[32:33], v[38:39]
	v_pk_mul_f32 v[34:35], v[34:35], v[160:161] op_sel:[0,1]
	v_cvt_pk_bf16_f32 v38, v32, v33
	v_pk_mul_f32 v[32:33], v[42:43], v[40:41]
	v_pk_mul_f32 v[28:29], v[28:29], v[154:155] op_sel_hi:[1,0]
	v_pk_mul_f32 v[32:33], v[34:35], v[32:33]
	s_mul_i32 s92, s64, 144
	v_lshl_add_u64 v[48:49], v[252:253], 0, s[92:93]
	v_cvt_pk_bf16_f32 v39, v32, v33
	v_mul_f32_e32 v34, 0xbfb8aa3b, v28
	v_mul_f32_e32 v35, 0xbfb8aa3b, v29
	v_exp_f32_e32 v34, v34
	v_exp_f32_e32 v35, v35
	v_pk_mul_f32 v[30:31], v[30:31], v[154:155] op_sel_hi:[1,0]
	global_store_dwordx4 v[48:49], v[36:39], off
	v_add_f32_e32 v34, 1.0, v34
	v_add_f32_e32 v35, 1.0, v35
	v_mul_f32_e32 v36, 0xbfb8aa3b, v30
	v_mul_f32_e32 v37, 0xbfb8aa3b, v31
	v_rcp_f32_e32 v34, v34
	v_rcp_f32_e32 v35, v35
	v_exp_f32_e32 v36, v36
	v_exp_f32_e32 v37, v37
	v_pk_mul_f32 v[20:21], v[20:21], v[154:155] op_sel_hi:[1,0]
	v_pk_mul_f32 v[28:29], v[28:29], v[34:35]
	v_add_f32_e32 v34, 1.0, v36
	v_add_f32_e32 v35, 1.0, v37
	v_rcp_f32_e32 v34, v34
	v_rcp_f32_e32 v35, v35
	v_pk_mul_f32 v[20:21], v[20:21], v[28:29]
	v_pk_mul_f32 v[24:25], v[24:25], v[154:155] op_sel_hi:[1,0]
	v_cvt_pk_bf16_f32 v20, v20, v21
	v_pk_mul_f32 v[28:29], v[30:31], v[34:35]
	v_pk_mul_f32 v[22:23], v[22:23], v[154:155] op_sel_hi:[1,0]
	v_mul_f32_e32 v21, 0xbfb8aa3b, v24
	v_pk_mul_f32 v[22:23], v[22:23], v[28:29]
	v_exp_f32_e32 v28, v21
	v_mul_f32_e32 v21, 0xbfb8aa3b, v25
	v_exp_f32_e32 v29, v21
	v_pk_mul_f32 v[26:27], v[26:27], v[154:155] op_sel_hi:[1,0]
	v_cvt_pk_bf16_f32 v21, v22, v23
	v_add_f32_e32 v22, 1.0, v28
	v_add_f32_e32 v23, 1.0, v29
	v_mul_f32_e32 v28, 0xbfb8aa3b, v26
	v_mul_f32_e32 v29, 0xbfb8aa3b, v27
	v_rcp_f32_e32 v22, v22
	v_rcp_f32_e32 v23, v23
	v_exp_f32_e32 v28, v28
	v_exp_f32_e32 v29, v29
	v_pk_mul_f32 v[16:17], v[16:17], v[154:155] op_sel_hi:[1,0]
	v_pk_mul_f32 v[22:23], v[24:25], v[22:23]
	v_add_f32_e32 v24, 1.0, v28
	v_add_f32_e32 v25, 1.0, v29
	v_rcp_f32_e32 v24, v24
	v_rcp_f32_e32 v25, v25
	v_pk_mul_f32 v[16:17], v[16:17], v[22:23]
	v_pk_mul_f32 v[18:19], v[18:19], v[154:155] op_sel_hi:[1,0]
	v_cvt_pk_bf16_f32 v22, v16, v17
	v_pk_mul_f32 v[16:17], v[26:27], v[24:25]
	v_pk_mul_f32 v[12:13], v[12:13], v[154:155] op_sel:[0,1]
	v_pk_mul_f32 v[16:17], v[18:19], v[16:17]
	s_mul_i32 s92, s64, 160
	v_lshl_add_u64 v[32:33], v[252:253], 0, s[92:93]
	v_cvt_pk_bf16_f32 v23, v16, v17
	v_mul_f32_e32 v18, 0xbfb8aa3b, v12
	v_mul_f32_e32 v19, 0xbfb8aa3b, v13
	v_exp_f32_e32 v18, v18
	v_exp_f32_e32 v19, v19
	v_pk_mul_f32 v[14:15], v[14:15], v[154:155] op_sel:[0,1]
	global_store_dwordx4 v[32:33], v[20:23], off
	v_add_f32_e32 v18, 1.0, v18
	v_add_f32_e32 v19, 1.0, v19
	v_mul_f32_e32 v20, 0xbfb8aa3b, v14
	v_mul_f32_e32 v21, 0xbfb8aa3b, v15
	v_rcp_f32_e32 v18, v18
	v_rcp_f32_e32 v19, v19
	v_exp_f32_e32 v20, v20
	v_exp_f32_e32 v21, v21
	v_pk_mul_f32 v[4:5], v[4:5], v[154:155] op_sel:[0,1]
	v_pk_mul_f32 v[12:13], v[12:13], v[18:19]
	v_add_f32_e32 v18, 1.0, v20
	v_add_f32_e32 v19, 1.0, v21
	v_rcp_f32_e32 v18, v18
	v_rcp_f32_e32 v19, v19
	v_pk_mul_f32 v[4:5], v[4:5], v[12:13]
	v_pk_mul_f32 v[8:9], v[8:9], v[154:155] op_sel:[0,1]
	v_cvt_pk_bf16_f32 v4, v4, v5
	v_pk_mul_f32 v[12:13], v[14:15], v[18:19]
	v_pk_mul_f32 v[6:7], v[6:7], v[154:155] op_sel:[0,1]
	v_mul_f32_e32 v5, 0xbfb8aa3b, v8
	v_pk_mul_f32 v[6:7], v[6:7], v[12:13]
	v_exp_f32_e32 v12, v5
	v_mul_f32_e32 v5, 0xbfb8aa3b, v9
	v_exp_f32_e32 v13, v5
	v_pk_mul_f32 v[10:11], v[10:11], v[154:155] op_sel:[0,1]
	v_cvt_pk_bf16_f32 v5, v6, v7
	v_add_f32_e32 v6, 1.0, v12
	v_add_f32_e32 v7, 1.0, v13
	v_mul_f32_e32 v12, 0xbfb8aa3b, v10
	v_mul_f32_e32 v13, 0xbfb8aa3b, v11
	v_rcp_f32_e32 v6, v6
	v_rcp_f32_e32 v7, v7
	v_exp_f32_e32 v12, v12
	v_exp_f32_e32 v13, v13
	v_pk_mul_f32 v[0:1], v[0:1], v[154:155] op_sel:[0,1]
	v_pk_mul_f32 v[6:7], v[8:9], v[6:7]
	v_add_f32_e32 v8, 1.0, v12
	v_add_f32_e32 v9, 1.0, v13
	v_rcp_f32_e32 v8, v8
	v_rcp_f32_e32 v9, v9
	v_pk_mul_f32 v[0:1], v[0:1], v[6:7]
	v_pk_mul_f32 v[2:3], v[2:3], v[154:155] op_sel:[0,1]
	v_cvt_pk_bf16_f32 v6, v0, v1
	v_pk_mul_f32 v[0:1], v[10:11], v[8:9]
	s_mul_i32 s92, s64, 176
	v_lshl_add_u64 v[16:17], v[252:253], 0, s[92:93]
	v_pk_mul_f32 v[0:1], v[2:3], v[0:1]
	s_andn2_b64 vcc, exec, s[6:7]
	v_cvt_pk_bf16_f32 v7, v0, v1
	s_mov_b64 s[0:1], -1
	global_store_dwordx4 v[16:17], v[4:7], off
	s_cbranch_vccnz .LBB0_502
	s_andn2_b64 vcc, exec, s[18:19]
	s_cbranch_vccnz .LBB0_501
	s_barrier
	s_branch .LBB0_501

	.amdhsa_kernel _Z10hybrid_fwd6Params
		.amdhsa_group_segment_fixed_size 0
		.amdhsa_private_segment_fixed_size 0
		.amdhsa_kernarg_size 440
		.amdhsa_user_sgpr_count 2
		.amdhsa_user_sgpr_dispatch_ptr 0
		.amdhsa_user_sgpr_queue_ptr 0
		.amdhsa_user_sgpr_kernarg_segment_ptr 1
		.amdhsa_user_sgpr_dispatch_id 0
		.amdhsa_user_sgpr_kernarg_preload_length 0
		.amdhsa_user_sgpr_kernarg_preload_offset 0
		.amdhsa_user_sgpr_private_segment_size 0
		.amdhsa_uses_dynamic_stack 0
		.amdhsa_enable_private_segment 0
		.amdhsa_system_sgpr_workgroup_id_x 1
		.amdhsa_system_sgpr_workgroup_id_y 0
		.amdhsa_system_sgpr_workgroup_id_z 0
		.amdhsa_system_sgpr_workgroup_info 0
		.amdhsa_system_vgpr_workitem_id 2
		.amdhsa_next_free_vgpr 256
		.amdhsa_next_free_sgpr 96
		.amdhsa_accum_offset 256
		.amdhsa_reserve_vcc 1
		.amdhsa_float_round_mode_32 0
		.amdhsa_float_round_mode_16_64 0
		.amdhsa_float_denorm_mode_32 3
		.amdhsa_float_denorm_mode_16_64 3
		.amdhsa_dx10_clamp 1
		.amdhsa_ieee_mode 1
		.amdhsa_fp16_overflow 0
		.amdhsa_tg_split 0
		.amdhsa_exception_fp_ieee_invalid_op 0
		.amdhsa_exception_fp_denorm_src 0
		.amdhsa_exception_fp_ieee_div_zero 0
		.amdhsa_exception_fp_ieee_overflow 0
		.amdhsa_exception_fp_ieee_underflow 0
		.amdhsa_exception_fp_ieee_inexact 0
		.amdhsa_exception_int_div_zero 0
	.end_amdhsa_kernel

amdhsa.kernels:
  - .agpr_count:     0
    .args:
      - .offset:         0
        .size:           184
        .value_kind:     by_value
      - .offset:         184
        .size:           4
        .value_kind:     hidden_block_count_x
      - .offset:         188
        .size:           4
        .value_kind:     hidden_block_count_y
      - .offset:         192
        .size:           4
        .value_kind:     hidden_block_count_z
      - .offset:         196
        .size:           2
        .value_kind:     hidden_group_size_x
      - .offset:         198
        .size:           2
        .value_kind:     hidden_group_size_y
      - .offset:         200
        .size:           2
        .value_kind:     hidden_group_size_z
      - .offset:         202
        .size:           2
        .value_kind:     hidden_remainder_x
      - .offset:         204
        .size:           2
        .value_kind:     hidden_remainder_y
      - .offset:         206
        .size:           2
        .value_kind:     hidden_remainder_z
      - .offset:         224
        .size:           8
        .value_kind:     hidden_global_offset_x
      - .offset:         232
        .size:           8
        .value_kind:     hidden_global_offset_y
      - .offset:         240
        .size:           8
        .value_kind:     hidden_global_offset_z
      - .offset:         248
        .size:           2
        .value_kind:     hidden_grid_dims
      - .offset:         272
        .size:           8
        .value_kind:     hidden_multigrid_sync_arg
      - .offset:         304
        .size:           4
        .value_kind:     hidden_dynamic_lds_size
    .group_segment_fixed_size: 0
    .kernarg_segment_align: 8
    .kernarg_segment_size: 440
    .language:       OpenCL C
    .language_version:
      - 2
      - 0
    .max_flat_workgroup_size: 512
    .name:           _Z10hybrid_fwd6Params
    .private_segment_fixed_size: 0
    .sgpr_count:     102
    .sgpr_spill_count: 0
    .symbol:         _Z10hybrid_fwd6Params.kd
    .uniform_work_group_size: 1
    .uses_dynamic_stack: false
    .vgpr_count:     256
    .vgpr_spill_count: 0
    .wavefront_size: 64
